# short-conv (yb) loop start staggered per wave (wave w sleeps w*0.25us) to spread the load bursts; on top of v067
# baseline (speedup 1.0000x reference)
; #define fresh_tid() ((wave0 << 6) | lane_id_fresh())
; __device__ __forceinline__ void yb_phase(const Ptrs& P, int G, int tid) {
;     for (int it = blockIdx.x * 512 + tid; it < (T / 8) * (HW / 8); it += G * 512) {
;         const int c = (it & 255) * 8, t0 = (it >> 8) * 8;
;         float w0[8], w1[8], w2[8], pm2[8], pm1[8];
; #pragma unroll
;         for (int q = 0; q < 2; ++q) { const f32x4 a = *(const f32x4*)(P.conv_w + c + 4 * q), b = *(const f32x4*)(P.conv_w + HW + c + 4 * q), cc = *(const f32x4*)(P.conv_w + 2 * HW + c + 4 * q);
; #pragma unroll
;             for (int j = 0; j < 4; ++j) { w0[4 * q + j] = a[j]; w1[4 * q + j] = b[j]; w2[4 * q + j] = cc[j]; } }
; template <int COOP>
; __global__ void __launch_bounds__(512, 2) mega(Args a) {
;     ...
;         __syncthreads();
;         yb_phase(P, G, fresh_tid());
.LBB0_234:
	s_barrier
	s_waitcnt vmcnt(0)
	s_lshr_b32 s90, s33, 6
	s_cmp_eq_u32 s90, 0
	s_cbranch_scc1 .Lybs_done
.Lybs_loop:
	s_sleep 8
	s_sub_i32 s90, s90, 1
	s_cmp_lg_u32 s90, 0
	s_cbranch_scc1 .Lybs_loop
.Lybs_done:
	v_mbcnt_lo_u32_b32 v0, -1, 0
	v_mbcnt_hi_u32_b32 v0, -1, v0
	s_mov_b32 s8, 0x40000
	v_or_b32_e32 v0, s33, v0
	v_add_u32_e32 v108, s52, v0
	v_cmp_gt_i32_e32 vcc, s8, v108
	s_and_saveexec_b64 s[8:9], vcc
	s_cbranch_execz .LBB0_239
	s_add_u32 s10, s28, 0x24200000
	s_addc_u32 s11, s7, 0
	s_add_u32 s12, s28, 0x26200000
	s_addc_u32 s13, s7, 0
	s_add_u32 s14, s28, 0x28200000
	s_addc_u32 s15, s7, 0
	s_add_u32 s16, s0, 0x2000
	s_addc_u32 s17, s1, 0
	s_add_u32 s18, s0, 0x4000
	v_lshlrev_b32_e32 v0, 3, v0
	s_addc_u32 s19, s1, 0
	v_lshl_add_u32 v109, s2, 12, v0
	s_lshl_b32 s7, s30, 12
	s_mov_b64 s[20:21], 0
	v_mov_b32_e32 v67, 0
	s_movk_i32 s24, 0x1000
	s_mov_b32 s25, 0x3ffff
	s_branch .LBB0_237
